# as v133 plus the four ssm pass loops moved by 56 bytes (padding in unexecuted space after unconditional branches; later code unshifted)
# baseline (speedup 1.0000x reference)
.LBB0_499:
	s_or_b64 exec, exec, s[10:11]
	s_ashr_i32 s10, s15, 5
	s_lshl_b32 s18, s10, 8
	v_lshlrev_b32_e32 v48, 3, v161
	v_readlane_b32 s11, v254, 15
	v_or_b32_e32 v49, s18, v89
	s_add_u32 s12, s11, s12
	v_readlane_b32 s11, v254, 16
	v_lshlrev_b32_e32 v49, 9, v49
	v_and_b32_e32 v84, 8, v48
	v_lshlrev_b32_e32 v85, 11, v161
	s_addc_u32 s13, s11, s13
	v_lshlrev_b32_e32 v70, 8, v89
	v_mov_b32_e32 v71, v137
	v_lshlrev_b32_e32 v72, 1, v48
	v_or3_b32 v48, v49, v84, s6
	s_lshl_b32 s11, s10, 17
	v_or_b32_e32 v49, s6, v85
	v_lshl_add_u64 v[32:33], s[12:13], 0, v[70:71]
	v_mov_b32_e32 v73, v137
	v_or3_b32 v50, v49, s11, v89
	v_lshl_add_u64 v[44:45], v[32:33], 0, v[72:73]
	v_lshlrev_b32_e32 v48, 1, v48
	v_lshlrev_b32_e32 v50, 1, v50
	s_or_b32 s11, s18, 16
	global_load_dwordx4 v[32:35], v[44:45], off
	global_load_dwordx4 v[36:39], v[44:45], off offset:64
	global_load_dwordx4 v[40:43], v[44:45], off offset:128
	s_nop 0
	global_load_dwordx4 v[44:47], v[44:45], off offset:192
	v_or_b32_e32 v51, 0x400, v50
	v_or_b32_e32 v52, 0x800, v50
	global_load_dwordx4 v[60:63], v48, s[84:85]
	global_load_ushort v106, v50, s[84:85]
	global_load_ushort v107, v51, s[84:85]
	global_load_ushort v108, v52, s[84:85]
	v_or_b32_e32 v48, 0xc00, v50
	v_or_b32_e32 v50, s11, v89
	s_lshl_b32 s11, s11, 9
	v_lshlrev_b32_e32 v50, 9, v50
	v_or3_b32 v51, v49, s11, v89
	v_or3_b32 v50, v50, v84, s6
	v_lshlrev_b32_e32 v51, 1, v51
	v_lshlrev_b32_e32 v50, 1, v50
	v_or_b32_e32 v56, 0x400, v51
	global_load_ushort v109, v48, s[84:85]
	global_load_dwordx4 v[52:55], v50, s[84:85]
	global_load_ushort v94, v51, s[84:85]
	global_load_ushort v95, v56, s[84:85]
	v_or_b32_e32 v48, 0x800, v51
	v_or_b32_e32 v50, 0xc00, v51
	global_load_ushort v96, v48, s[84:85]
	global_load_ushort v97, v50, s[84:85]
	v_lshlrev_b32_e32 v48, 10, v161
	v_lshlrev_b32_e32 v50, 2, v89
	v_mov_b32_e32 v51, s23
	s_movk_i32 s11, 0x110
	v_and_b32_e32 v56, 48, v88
	v_lshlrev_b32_e32 v57, 1, v89
	v_lshlrev_b32_e32 v58, 10, v89
	v_and_b32_e32 v59, 16, v160
	v_lshlrev_b32_e32 v79, 12, v161
	v_add3_u32 v65, s23, v48, v50
	v_mad_u32_u24 v48, v89, s11, v51
	s_lshl_b32 s11, s17, 5
	v_lshlrev_b32_e32 v66, 2, v160
	v_add_lshl_u32 v76, v49, v89, 1
	v_add_u32_e32 v77, v48, v56
	v_or3_b32 v78, v58, s11, v59
	v_or3_b32 v79, v79, s11, v57
	v_mov_b32_e32 v104, 0
	v_mov_b32_e32 v105, 0
	v_add_u32_e32 v75, s23, v66
	s_lshl_b32 s16, s10, 18
	v_mov_b32_e32 v73, v76
	v_mov_b32_e32 v86, v79
	v_mov_b32_e32 v87, v78
	s_waitcnt vmcnt(0)
	v_mov_b64_e32 v[48:49], v[60:61]
	v_mov_b64_e32 v[50:51], v[62:63]
	v_mov_b32_e32 v90, v106
	v_mov_b32_e32 v91, v107
	v_mov_b32_e32 v92, v108
	v_mov_b32_e32 v93, v109
	s_branch .LBB0_501
	s_nop 0
	s_nop 0
	s_nop 0
	s_nop 0
	s_nop 0
	s_nop 0
	s_nop 0
	s_nop 0
	s_nop 0
	s_nop 0
	s_nop 0
	s_nop 0
	s_nop 0
	s_nop 0

.LBB0_503:
	v_cndmask_b32_e64 v59, 0, v63, s[8:9]
	v_cndmask_b32_e64 v58, 0, v62, s[8:9]
	v_cndmask_b32_e64 v57, 0, v61, s[8:9]
	v_cndmask_b32_e64 v56, 0, v60, s[8:9]
	v_lshlrev_b32_e32 v106, 16, v106
	v_lshlrev_b32_e32 v107, 16, v107
	v_mfma_f32_16x16x32_bf16 v[60:63], v[56:59], v[4:7], 0
	v_lshlrev_b32_e32 v108, 16, v108
	v_lshlrev_b32_e32 v109, 16, v109
	s_cmp_gt_u32 s14, 12
	v_mfma_f32_16x16x32_bf16 v[80:83], v[56:59], v[0:3], 0
	s_nop 7
	v_cvt_pkrtz_f16_f32 v100, v60, v80
	v_cvt_pkrtz_f16_f32 v101, v61, v81
	v_cvt_pkrtz_f16_f32 v102, v62, v82
	v_cvt_pkrtz_f16_f32 v103, v63, v83
	v_mfma_f32_16x16x32_bf16 v[60:63], v[56:59], v[12:15], 0
	v_mfma_f32_16x16x32_bf16 v[80:83], v[56:59], v[8:11], 0
	s_nop 7
	v_cvt_pkrtz_f16_f32 v60, v60, v80
	ds_write2_b32 v65, v100, v60 offset1:16
	v_cvt_pkrtz_f16_f32 v60, v61, v81
	ds_write2_b32 v65, v101, v60 offset0:64 offset1:80
	v_cvt_pkrtz_f16_f32 v60, v62, v82
	ds_write2_b32 v65, v102, v60 offset0:128 offset1:144
	v_cvt_pkrtz_f16_f32 v60, v63, v83
	ds_write2_b32 v65, v103, v60 offset0:192 offset1:208
	v_mfma_f32_16x16x32_bf16 v[60:63], v[56:59], v[20:23], 0
	v_mfma_f32_16x16x32_bf16 v[80:83], v[56:59], v[16:19], 0
	s_nop 7
	v_cvt_pkrtz_f16_f32 v80, v60, v80
	v_cvt_pkrtz_f16_f32 v81, v61, v81
	v_cvt_pkrtz_f16_f32 v82, v62, v82
	v_cvt_pkrtz_f16_f32 v83, v63, v83
	v_mfma_f32_16x16x32_bf16 v[60:63], v[56:59], v[28:31], 0
	v_mfma_f32_16x16x32_bf16 v[56:59], v[56:59], v[24:27], 0
	s_nop 7
	v_cvt_pkrtz_f16_f32 v56, v60, v56
	ds_write2_b32 v65, v80, v56 offset0:32 offset1:48
	v_cvt_pkrtz_f16_f32 v56, v61, v57
	ds_write2_b32 v65, v81, v56 offset0:96 offset1:112
	v_cvt_pkrtz_f16_f32 v56, v62, v58
	ds_write2_b32 v65, v82, v56 offset0:160 offset1:176
	v_cvt_pkrtz_f16_f32 v56, v63, v59
	ds_write2_b32 v65, v83, v56 offset0:224 offset1:240
	ds_read2st64_b32 v[56:57], v75 offset1:1
	ds_read2st64_b32 v[58:59], v75 offset0:2 offset1:3
	ds_read2st64_b32 v[60:61], v75 offset0:4 offset1:5
	ds_read2st64_b32 v[62:63], v75 offset0:6 offset1:7
	ds_read2st64_b32 v[80:81], v75 offset0:8 offset1:9
	ds_read2st64_b32 v[82:83], v75 offset0:10 offset1:11
	ds_read2st64_b32 v[100:101], v75 offset0:12 offset1:13
	ds_read2st64_b32 v[102:103], v75 offset0:14 offset1:15
	s_waitcnt lgkmcnt(7)
	v_fma_mix_f32 v110, v68, v104, v56 op_sel_hi:[0,0,1]
	v_fma_mix_f32 v56, v68, v105, v56 op_sel:[0,0,1] op_sel_hi:[0,0,1]
	v_fma_f32 v105, -v69, v105, v110
	v_fmac_f32_e32 v56, v69, v104
	s_nop 0
	v_fma_mix_f32 v110, v68, v105, v57 op_sel_hi:[0,0,1]
	v_fma_mix_f32 v57, v68, v56, v57 op_sel:[0,0,1] op_sel_hi:[0,0,1]
	v_cvt_pk_bf16_f32 v104, v105, v56
	v_fma_f32 v56, -v69, v56, v110
	v_fmac_f32_e32 v57, v69, v105
	s_waitcnt lgkmcnt(6)
	v_fma_mix_f32 v110, v68, v56, v58 op_sel_hi:[0,0,1]
	v_fma_mix_f32 v58, v68, v57, v58 op_sel:[0,0,1] op_sel_hi:[0,0,1]
	v_cvt_pk_bf16_f32 v105, v56, v57
	v_fma_f32 v57, -v69, v57, v110
	v_fmac_f32_e32 v58, v69, v56
	s_nop 0
	v_fma_mix_f32 v110, v68, v57, v59 op_sel_hi:[0,0,1]
	v_fma_mix_f32 v59, v68, v58, v59 op_sel:[0,0,1] op_sel_hi:[0,0,1]
	v_cvt_pk_bf16_f32 v56, v57, v58
	v_fma_f32 v58, -v69, v58, v110
	v_fmac_f32_e32 v59, v69, v57
	s_waitcnt lgkmcnt(5)
	v_fma_mix_f32 v110, v68, v58, v60 op_sel_hi:[0,0,1]
	v_fma_mix_f32 v60, v68, v59, v60 op_sel:[0,0,1] op_sel_hi:[0,0,1]
	v_cvt_pk_bf16_f32 v57, v58, v59
	v_fma_f32 v59, -v69, v59, v110
	v_fmac_f32_e32 v60, v69, v58
	s_nop 0
	v_fma_mix_f32 v110, v68, v59, v61 op_sel_hi:[0,0,1]
	v_fma_mix_f32 v61, v68, v60, v61 op_sel:[0,0,1] op_sel_hi:[0,0,1]
	v_cvt_pk_bf16_f32 v58, v59, v60
	v_fma_f32 v60, -v69, v60, v110
	v_fmac_f32_e32 v61, v69, v59
	s_waitcnt lgkmcnt(4)
	v_fma_mix_f32 v110, v68, v60, v62 op_sel_hi:[0,0,1]
	v_fma_mix_f32 v62, v68, v61, v62 op_sel:[0,0,1] op_sel_hi:[0,0,1]
	v_cvt_pk_bf16_f32 v59, v60, v61
	v_fma_f32 v61, -v69, v61, v110
	v_fmac_f32_e32 v62, v69, v60
	s_nop 0
	v_fma_mix_f32 v110, v68, v61, v63 op_sel_hi:[0,0,1]
	v_fma_mix_f32 v63, v68, v62, v63 op_sel:[0,0,1] op_sel_hi:[0,0,1]
	v_cvt_pk_bf16_f32 v60, v61, v62
	v_fma_f32 v62, -v69, v62, v110
	v_fmac_f32_e32 v63, v69, v61
	s_waitcnt lgkmcnt(3)
	v_fma_mix_f32 v61, v68, v62, v80 op_sel_hi:[0,0,1]
	v_fma_mix_f32 v80, v68, v63, v80 op_sel:[0,0,1] op_sel_hi:[0,0,1]
	v_fma_f32 v61, -v69, v63, v61
	v_fmac_f32_e32 v80, v69, v62
	v_cvt_pk_bf16_f32 v110, v62, v63
	s_nop 0
	v_fma_mix_f32 v62, v68, v61, v81 op_sel_hi:[0,0,1]
	v_fma_mix_f32 v81, v68, v80, v81 op_sel:[0,0,1] op_sel_hi:[0,0,1]
	v_fma_f32 v62, -v69, v80, v62
	v_fmac_f32_e32 v81, v69, v61
	v_cvt_pk_bf16_f32 v63, v61, v80
	s_waitcnt lgkmcnt(2)
	v_fma_mix_f32 v61, v68, v62, v82 op_sel_hi:[0,0,1]
	v_fma_mix_f32 v80, v68, v81, v82 op_sel:[0,0,1] op_sel_hi:[0,0,1]
	v_fma_f32 v61, -v69, v81, v61
	v_fmac_f32_e32 v80, v69, v62
	v_cvt_pk_bf16_f32 v111, v62, v81
	v_add_u32_e32 v82, 0x2800, v75
	v_fma_mix_f32 v62, v68, v61, v83 op_sel_hi:[0,0,1]
	v_fma_mix_f32 v81, v68, v80, v83 op_sel:[0,0,1] op_sel_hi:[0,0,1]
	v_fma_f32 v62, -v69, v80, v62
	v_fmac_f32_e32 v81, v69, v61
	v_cvt_pk_bf16_f32 v112, v61, v80
	s_waitcnt lgkmcnt(1)
	v_fma_mix_f32 v61, v68, v62, v100 op_sel_hi:[0,0,1]
	v_fma_mix_f32 v80, v68, v81, v100 op_sel:[0,0,1] op_sel_hi:[0,0,1]
	v_fma_f32 v61, -v69, v81, v61
	v_fmac_f32_e32 v80, v69, v62
	v_cvt_pk_bf16_f32 v83, v62, v81
	s_nop 0
	v_fma_mix_f32 v62, v68, v61, v101 op_sel_hi:[0,0,1]
	v_fma_mix_f32 v81, v68, v80, v101 op_sel:[0,0,1] op_sel_hi:[0,0,1]
	v_fma_f32 v62, -v69, v80, v62
	v_fmac_f32_e32 v81, v69, v61
	v_cvt_pk_bf16_f32 v100, v61, v80
	s_waitcnt lgkmcnt(0)
	v_fma_mix_f32 v61, v68, v62, v102 op_sel_hi:[0,0,1]
	v_fma_mix_f32 v80, v68, v81, v102 op_sel:[0,0,1] op_sel_hi:[0,0,1]
	v_cvt_pk_bf16_f32 v101, v62, v81
	v_fma_f32 v81, -v69, v81, v61
	v_fmac_f32_e32 v80, v69, v62
	s_nop 0
	v_fma_mix_f32 v61, v68, v81, v103 op_sel_hi:[0,0,1]
	v_fma_mix_f32 v62, v68, v80, v103 op_sel:[0,0,1] op_sel_hi:[0,0,1]
	v_cvt_pk_bf16_f32 v102, v81, v80
	v_fma_f32 v61, -v69, v80, v61
	v_fmac_f32_e32 v62, v69, v81
	v_add_u32_e32 v80, 0x2000, v75
	v_add_u32_e32 v81, 0x2400, v75
	s_nop 0
	v_cvt_pk_bf16_f32 v103, v61, v62
	ds_write2_b32 v80, v104, v105 offset1:68
	ds_write2_b32 v80, v56, v57 offset0:136 offset1:204
	ds_write2_b32 v81, v58, v59 offset0:16 offset1:84
	ds_write2_b32 v81, v60, v110 offset0:152 offset1:220
	ds_write2_b32 v82, v63, v111 offset0:32 offset1:100
	ds_write2_b32 v82, v112, v83 offset0:168 offset1:236
	v_add_u32_e32 v83, 0x2c00, v75
	ds_write2_b32 v83, v100, v101 offset0:48 offset1:116
	ds_write2_b32 v83, v102, v103 offset0:184 offset1:252
	ds_read_b128 v[56:59], v77 offset:8192
	ds_read_b128 v[100:103], v77 offset:8256
	s_waitcnt lgkmcnt(1)
	v_mfma_f32_16x16x32_bf16 v[56:59], v[56:59], v[32:35], 0
	s_waitcnt lgkmcnt(0)
	v_mfma_f32_16x16x32_bf16 v[56:59], v[100:103], v[36:39], v[56:59]
	ds_read_b128 v[100:103], v77 offset:8320
	s_waitcnt lgkmcnt(0)
	v_mfma_f32_16x16x32_bf16 v[56:59], v[100:103], v[40:43], v[56:59]
	ds_read_b128 v[100:103], v77 offset:8384
	s_waitcnt lgkmcnt(0)
	v_mfma_f32_16x16x32_bf16 v[56:59], v[100:103], v[44:47], v[56:59]
	v_mov_b32_e32 v103, v97
	v_mov_b32_e32 v102, v96
	v_mov_b32_e32 v101, v95
	s_nop 4
	v_fma_f32 v56, v67, v106, v56
	v_bfe_u32 v60, v56, 16, 1
	v_add3_u32 v56, v56, v60, s90
	v_add_u32_e32 v60, s16, v86
	global_store_short_d16_hi v60, v56, s[4:5]
	v_fma_f32 v56, v67, v107, v57
	v_bfe_u32 v57, v56, 16, 1
	v_add3_u32 v56, v56, v57, s90
	v_add_u32_e32 v57, 0x400, v60
	global_store_short_d16_hi v57, v56, s[4:5]
	v_fma_f32 v56, v67, v108, v58
	v_bfe_u32 v57, v56, 16, 1
	v_add3_u32 v56, v56, v57, s90
	v_add_u32_e32 v57, 0x800, v60
	v_fmac_f32_e32 v59, v67, v109
	global_store_short_d16_hi v57, v56, s[4:5]
	v_bfe_u32 v56, v59, 16, 1
	v_add3_u32 v56, v59, v56, s90
	v_add_u32_e32 v57, 0xc00, v60
	global_store_short_d16_hi v57, v56, s[4:5]
	v_mov_b64_e32 v[58:59], v[54:55]
	v_mov_b32_e32 v100, v94
	v_mov_b64_e32 v[56:57], v[52:53]
	s_cbranch_scc1 .LBB0_500
	v_add_u32_e32 v56, 0xc000, v99
	v_add_u32_e32 v102, 0xc800, v98
	v_add_u32_e32 v63, 0xc000, v98
	v_add_u32_e32 v99, 0xc400, v98
	global_load_dwordx4 v[56:59], v56, s[84:85]
	s_nop 0
	global_load_ushort v100, v63, s[84:85]
	global_load_ushort v101, v99, s[84:85]
	s_nop 0
	global_load_ushort v102, v102, s[84:85]
	v_add_u32_e32 v63, 0xcc00, v98
	global_load_ushort v103, v63, s[84:85]
	s_branch .LBB0_500
	s_nop 0
	s_nop 0

.LBB0_521:
	s_or_b64 exec, exec, s[14:15]
	s_lshl_b32 s14, s17, 6
	v_readlane_b32 s15, v254, 15
	s_add_u32 s12, s15, s12
	v_readlane_b32 s15, v254, 16
	s_addc_u32 s13, s15, s13
	v_lshl_add_u64 v[32:33], s[12:13], 0, v[70:71]
	s_or_b32 s12, s18, 0xf0
	v_or_b32_e32 v48, s12, v89
	v_lshl_or_b32 v49, s12, 9, v85
	v_lshlrev_b32_e32 v48, 9, v48
	v_or3_b32 v49, v49, s6, v89
	v_mov_b32_e32 v73, v137
	v_or3_b32 v48, v48, v84, s6
	v_lshlrev_b32_e32 v49, 1, v49
	v_lshl_add_u64 v[44:45], v[32:33], 0, v[72:73]
	v_lshlrev_b32_e32 v48, 1, v48
	v_add_u32_e32 v50, 0x400, v49
	s_or_b32 s12, s18, 0xe0
	global_load_dwordx4 v[32:35], v[44:45], off
	global_load_dwordx4 v[36:39], v[44:45], off offset:64
	global_load_dwordx4 v[40:43], v[44:45], off offset:128
	s_nop 0
	global_load_dwordx4 v[44:47], v[44:45], off offset:192
	v_add_u32_e32 v51, 0x800, v49
	global_load_dwordx4 v[60:63], v48, s[84:85]
	global_load_ushort v97, v49, s[4:5]
	global_load_ushort v98, v50, s[4:5]
	global_load_ushort v99, v51, s[4:5]
	v_add_u32_e32 v48, 0xc00, v49
	v_or_b32_e32 v49, s12, v89
	v_lshl_or_b32 v50, s12, 9, v85
	v_lshlrev_b32_e32 v49, 9, v49
	v_or3_b32 v50, v50, s6, v89
	v_or3_b32 v49, v49, v84, s6
	v_lshlrev_b32_e32 v50, 1, v50
	v_lshlrev_b32_e32 v49, 1, v49
	v_add_u32_e32 v51, 0x400, v50
	global_load_ushort v100, v48, s[4:5]
	global_load_dwordx4 v[52:55], v49, s[84:85]
	global_load_ushort v73, v50, s[4:5]
	global_load_ushort v84, v51, s[4:5]
	v_add_u32_e32 v48, 0x800, v50
	v_add_u32_e32 v49, 0xc00, v50
	global_load_ushort v85, v48, s[4:5]
	global_load_ushort v86, v49, s[4:5]
	v_mov_b32_e32 v96, 0
	v_mov_b32_e32 v95, 0
	s_waitcnt vmcnt(9)
	v_mov_b64_e32 v[48:49], v[60:61]
	s_waitcnt vmcnt(8)
	v_mov_b32_e32 v72, v97
	s_waitcnt vmcnt(7)
	v_mov_b32_e32 v70, v98
	s_waitcnt vmcnt(6)
	v_mov_b32_e32 v67, v99
	v_mov_b64_e32 v[50:51], v[62:63]
	s_waitcnt vmcnt(5)
	v_mov_b32_e32 v71, v100
	s_branch .LBB0_523
	s_nop 0
	s_nop 0
	s_nop 0
	s_nop 0
	s_nop 0
	s_nop 0
	s_nop 0
	s_nop 0
	s_nop 0
	s_nop 0
	s_nop 0
	s_nop 0
	s_nop 0
	s_nop 0

.LBB0_525:
	v_cndmask_b32_e64 v63, 0, v63, s[8:9]
	v_cndmask_b32_e64 v62, 0, v62, s[8:9]
	v_cndmask_b32_e64 v61, 0, v61, s[8:9]
	v_cndmask_b32_e64 v60, 0, v60, s[8:9]
	v_lshlrev_b32_e32 v56, 16, v100
	v_lshlrev_b32_e32 v57, 16, v99
	v_lshlrev_b32_e32 v91, 16, v98
	v_mfma_f32_16x16x32_bf16 v[98:101], v[60:63], v[4:7], 0
	v_lshlrev_b32_e32 v106, 16, v97
	s_cmp_gt_u32 s19, 12
	v_mfma_f32_16x16x32_bf16 v[102:105], v[60:63], v[0:3], 0
	s_nop 7
	v_cvt_pkrtz_f16_f32 v58, v98, v102
	v_cvt_pkrtz_f16_f32 v59, v99, v103
	v_cvt_pkrtz_f16_f32 v92, v100, v104
	v_cvt_pkrtz_f16_f32 v93, v101, v105
	v_mfma_f32_16x16x32_bf16 v[98:101], v[60:63], v[12:15], 0
	v_mfma_f32_16x16x32_bf16 v[102:105], v[60:63], v[8:11], 0
	s_nop 7
	v_cvt_pkrtz_f16_f32 v94, v98, v102
	ds_write2_b32 v65, v58, v94 offset1:16
	v_cvt_pkrtz_f16_f32 v58, v99, v103
	ds_write2_b32 v65, v59, v58 offset0:64 offset1:80
	v_cvt_pkrtz_f16_f32 v58, v100, v104
	ds_write2_b32 v65, v92, v58 offset0:128 offset1:144
	v_cvt_pkrtz_f16_f32 v58, v101, v105
	v_mfma_f32_16x16x32_bf16 v[98:101], v[60:63], v[20:23], 0
	ds_write2_b32 v65, v93, v58 offset0:192 offset1:208
	v_mfma_f32_16x16x32_bf16 v[102:105], v[60:63], v[16:19], 0
	s_nop 7
	v_cvt_pkrtz_f16_f32 v92, v98, v102
	v_cvt_pkrtz_f16_f32 v93, v99, v103
	v_cvt_pkrtz_f16_f32 v94, v100, v104
	v_cvt_pkrtz_f16_f32 v97, v101, v105
	v_mfma_f32_16x16x32_bf16 v[98:101], v[60:63], v[28:31], 0
	v_mfma_f32_16x16x32_bf16 v[58:61], v[60:63], v[24:27], 0
	s_nop 7
	v_cvt_pkrtz_f16_f32 v58, v98, v58
	ds_write2_b32 v65, v92, v58 offset0:32 offset1:48
	v_cvt_pkrtz_f16_f32 v58, v99, v59
	ds_write2_b32 v65, v93, v58 offset0:96 offset1:112
	v_cvt_pkrtz_f16_f32 v58, v100, v60
	ds_write2_b32 v65, v94, v58 offset0:160 offset1:176
	v_cvt_pkrtz_f16_f32 v58, v101, v61
	ds_write2_b32 v65, v97, v58 offset0:224 offset1:240
	ds_read2st64_b32 v[58:59], v75 offset0:14 offset1:15
	ds_read2st64_b32 v[60:61], v75 offset0:12 offset1:13
	ds_read2st64_b32 v[62:63], v75 offset0:10 offset1:11
	ds_read2st64_b32 v[92:93], v75 offset0:8 offset1:9
	ds_read2st64_b32 v[98:99], v75 offset0:6 offset1:7
	ds_read2st64_b32 v[100:101], v75 offset0:4 offset1:5
	ds_read2st64_b32 v[102:103], v75 offset0:2 offset1:3
	ds_read2st64_b32 v[104:105], v75 offset1:1
	s_waitcnt lgkmcnt(7)
	v_fma_mix_f32 v94, v68, v96, v59 op_sel_hi:[0,0,1]
	v_fma_mix_f32 v59, v68, v95, v59 op_sel:[0,0,1] op_sel_hi:[0,0,1]
	v_fma_f32 v94, -v69, v95, v94
	v_fmac_f32_e32 v59, v69, v96
	s_nop 0
	v_fma_mix_f32 v96, v68, v94, v58 op_sel_hi:[0,0,1]
	v_fma_mix_f32 v58, v68, v59, v58 op_sel:[0,0,1] op_sel_hi:[0,0,1]
	v_cvt_pk_bf16_f32 v95, v94, v59
	v_fma_f32 v59, -v69, v59, v96
	v_fmac_f32_e32 v58, v69, v94
	s_waitcnt lgkmcnt(6)
	v_fma_mix_f32 v96, v68, v59, v61 op_sel_hi:[0,0,1]
	v_fma_mix_f32 v61, v68, v58, v61 op_sel:[0,0,1] op_sel_hi:[0,0,1]
	v_cvt_pk_bf16_f32 v94, v59, v58
	v_fma_f32 v58, -v69, v58, v96
	v_fmac_f32_e32 v61, v69, v59
	s_nop 0
	v_fma_mix_f32 v96, v68, v58, v60 op_sel_hi:[0,0,1]
	v_fma_mix_f32 v60, v68, v61, v60 op_sel:[0,0,1] op_sel_hi:[0,0,1]
	v_cvt_pk_bf16_f32 v59, v58, v61
	v_fma_f32 v61, -v69, v61, v96
	v_fmac_f32_e32 v60, v69, v58
	s_waitcnt lgkmcnt(5)
	v_fma_mix_f32 v96, v68, v61, v63 op_sel_hi:[0,0,1]
	v_fma_mix_f32 v63, v68, v60, v63 op_sel:[0,0,1] op_sel_hi:[0,0,1]
	v_cvt_pk_bf16_f32 v58, v61, v60
	v_fma_f32 v60, -v69, v60, v96
	v_fmac_f32_e32 v63, v69, v61
	s_nop 0
	v_fma_mix_f32 v61, v68, v60, v62 op_sel_hi:[0,0,1]
	v_fma_mix_f32 v62, v68, v63, v62 op_sel:[0,0,1] op_sel_hi:[0,0,1]
	v_fma_f32 v61, -v69, v63, v61
	v_fmac_f32_e32 v62, v69, v60
	v_cvt_pk_bf16_f32 v96, v60, v63
	s_waitcnt lgkmcnt(4)
	v_fma_mix_f32 v63, v68, v61, v93 op_sel_hi:[0,0,1]
	v_fma_mix_f32 v93, v68, v62, v93 op_sel:[0,0,1] op_sel_hi:[0,0,1]
	v_cvt_pk_bf16_f32 v60, v61, v62
	v_fma_f32 v62, -v69, v62, v63
	v_fmac_f32_e32 v93, v69, v61
	s_nop 0
	v_fma_mix_f32 v61, v68, v62, v92 op_sel_hi:[0,0,1]
	v_fma_mix_f32 v92, v68, v93, v92 op_sel:[0,0,1] op_sel_hi:[0,0,1]
	v_fma_f32 v61, -v69, v93, v61
	v_fmac_f32_e32 v92, v69, v62
	v_cvt_pk_bf16_f32 v63, v62, v93
	s_waitcnt lgkmcnt(3)
	v_fma_mix_f32 v62, v68, v61, v99 op_sel_hi:[0,0,1]
	v_fma_mix_f32 v97, v68, v92, v99 op_sel:[0,0,1] op_sel_hi:[0,0,1]
	v_fma_f32 v62, -v69, v92, v62
	v_fmac_f32_e32 v97, v69, v61
	v_cvt_pk_bf16_f32 v93, v61, v92
	s_nop 0
	v_fma_mix_f32 v61, v68, v62, v98 op_sel_hi:[0,0,1]
	v_fma_mix_f32 v98, v68, v97, v98 op_sel:[0,0,1] op_sel_hi:[0,0,1]
	v_fma_f32 v61, -v69, v97, v61
	v_fmac_f32_e32 v98, v69, v62
	v_cvt_pk_bf16_f32 v92, v62, v97
	s_waitcnt lgkmcnt(2)
	v_fma_mix_f32 v62, v68, v61, v101 op_sel_hi:[0,0,1]
	v_fma_mix_f32 v99, v68, v98, v101 op_sel:[0,0,1] op_sel_hi:[0,0,1]
	v_fma_f32 v62, -v69, v98, v62
	v_fmac_f32_e32 v99, v69, v61
	v_cvt_pk_bf16_f32 v97, v61, v98
	s_nop 0
	v_fma_mix_f32 v61, v68, v62, v100 op_sel_hi:[0,0,1]
	v_fma_mix_f32 v100, v68, v99, v100 op_sel:[0,0,1] op_sel_hi:[0,0,1]
	v_fma_f32 v61, -v69, v99, v61
	v_fmac_f32_e32 v100, v69, v62
	v_cvt_pk_bf16_f32 v98, v62, v99
	s_waitcnt lgkmcnt(1)
	v_fma_mix_f32 v62, v68, v61, v103 op_sel_hi:[0,0,1]
	v_fma_mix_f32 v101, v68, v100, v103 op_sel:[0,0,1] op_sel_hi:[0,0,1]
	v_fma_f32 v62, -v69, v100, v62
	v_fmac_f32_e32 v101, v69, v61
	v_cvt_pk_bf16_f32 v99, v61, v100
	s_nop 0
	v_fma_mix_f32 v61, v68, v62, v102 op_sel_hi:[0,0,1]
	v_fma_mix_f32 v102, v68, v101, v102 op_sel:[0,0,1] op_sel_hi:[0,0,1]
	v_fma_f32 v61, -v69, v101, v61
	v_fmac_f32_e32 v102, v69, v62
	v_cvt_pk_bf16_f32 v100, v62, v101
	s_waitcnt lgkmcnt(0)
	v_fma_mix_f32 v62, v68, v61, v105 op_sel_hi:[0,0,1]
	v_fma_mix_f32 v103, v68, v102, v105 op_sel:[0,0,1] op_sel_hi:[0,0,1]
	v_cvt_pk_bf16_f32 v101, v61, v102
	v_fma_f32 v102, -v69, v102, v62
	v_fmac_f32_e32 v103, v69, v61
	s_nop 0
	v_fma_mix_f32 v61, v68, v102, v104 op_sel_hi:[0,0,1]
	v_fma_mix_f32 v62, v68, v103, v104 op_sel:[0,0,1] op_sel_hi:[0,0,1]
	v_fma_f32 v61, -v69, v103, v61
	v_fmac_f32_e32 v62, v69, v102
	v_cvt_pk_bf16_f32 v105, v102, v103
	s_nop 0
	v_cvt_pk_bf16_f32 v102, v61, v62
	ds_write2_b32 v83, v94, v95 offset0:184 offset1:252
	ds_write2_b32 v83, v58, v59 offset0:48 offset1:116
	ds_write2_b32 v82, v60, v96 offset0:168 offset1:236
	ds_write2_b32 v82, v93, v63 offset0:32 offset1:100
	ds_write2_b32 v81, v97, v92 offset0:152 offset1:220
	ds_write2_b32 v81, v99, v98 offset0:16 offset1:84
	ds_write2_b32 v80, v101, v100 offset0:136 offset1:204
	ds_write2_b32 v80, v102, v105 offset1:68
	ds_read_b128 v[92:95], v77 offset:8192
	ds_read_b128 v[96:99], v77 offset:8256
	s_waitcnt lgkmcnt(1)
	v_mfma_f32_16x16x32_bf16 v[92:95], v[92:95], v[32:35], 0
	v_add_u32_e32 v60, s16, v79
	s_waitcnt lgkmcnt(0)
	v_mfma_f32_16x16x32_bf16 v[92:95], v[96:99], v[36:39], v[92:95]
	ds_read_b128 v[96:99], v77 offset:8320
	s_waitcnt lgkmcnt(0)
	v_mfma_f32_16x16x32_bf16 v[92:95], v[96:99], v[40:43], v[92:95]
	ds_read_b128 v[96:99], v77 offset:8384
	s_waitcnt lgkmcnt(0)
	v_mfma_f32_16x16x32_bf16 v[92:95], v[96:99], v[44:47], v[92:95]
	s_nop 7
	v_add_f32_e32 v58, v92, v106
	v_mul_f32_e32 v59, 0x3d372713, v58
	v_mul_f32_e32 v59, v58, v59
	v_fma_f32 v59, v58, v59, v58
	v_mul_f32_e32 v59, 0x3f4c422a, v59
	v_add_f32_e32 v59, v59, v59
	v_mul_f32_e32 v59, 0xbfb8aa3b, v59
	v_exp_f32_e32 v59, v59
	v_add_f32_e32 v57, v94, v57
	v_add_f32_e32 v56, v95, v56
	s_waitcnt vmcnt(0)
	v_mov_b32_e32 v94, v86
	v_add_f32_e32 v59, 1.0, v59
	v_rcp_f32_e32 v59, v59
	v_mov_b32_e32 v92, v84
	v_mul_f32_e32 v58, v58, v59
	v_bfe_u32 v59, v58, 16, 1
	v_add3_u32 v58, v58, v59, s90
	v_add_u32_e32 v59, 0x3c000, v60
	global_store_short_d16_hi v59, v58, s[0:1]
	v_add_f32_e32 v58, v93, v91
	v_mul_f32_e32 v59, 0x3d372713, v58
	v_mul_f32_e32 v59, v58, v59
	v_fma_f32 v59, v58, v59, v58
	v_mul_f32_e32 v59, 0x3f4c422a, v59
	v_add_f32_e32 v59, v59, v59
	v_mul_f32_e32 v59, 0xbfb8aa3b, v59
	v_exp_f32_e32 v59, v59
	v_mov_b32_e32 v93, v85
	v_mov_b32_e32 v91, v73
	v_add_f32_e32 v59, 1.0, v59
	v_rcp_f32_e32 v59, v59
	s_nop 0
	v_mul_f32_e32 v58, v58, v59
	v_bfe_u32 v59, v58, 16, 1
	v_add3_u32 v58, v58, v59, s90
	v_add_u32_e32 v59, 0x3c400, v60
	global_store_short_d16_hi v59, v58, s[0:1]
	v_mul_f32_e32 v58, 0x3d372713, v57
	v_mul_f32_e32 v58, v57, v58
	v_fma_f32 v58, v57, v58, v57
	v_mul_f32_e32 v58, 0x3f4c422a, v58
	v_add_f32_e32 v58, v58, v58
	v_mul_f32_e32 v58, 0xbfb8aa3b, v58
	v_exp_f32_e32 v58, v58
	s_nop 0
	v_add_f32_e32 v58, 1.0, v58
	v_rcp_f32_e32 v58, v58
	s_nop 0
	v_mul_f32_e32 v57, v57, v58
	v_bfe_u32 v58, v57, 16, 1
	v_add3_u32 v57, v57, v58, s90
	v_add_u32_e32 v58, 0x3c800, v60
	global_store_short_d16_hi v58, v57, s[0:1]
	v_mul_f32_e32 v57, 0x3d372713, v56
	v_mul_f32_e32 v57, v56, v57
	v_fma_f32 v57, v56, v57, v56
	v_mul_f32_e32 v57, 0x3f4c422a, v57
	v_add_f32_e32 v57, v57, v57
	v_mul_f32_e32 v57, 0xbfb8aa3b, v57
	v_exp_f32_e32 v57, v57
	s_nop 0
	v_add_f32_e32 v57, 1.0, v57
	v_rcp_f32_e32 v57, v57
	s_nop 0
	v_mul_f32_e32 v56, v56, v57
	v_bfe_u32 v57, v56, 16, 1
	v_add3_u32 v56, v56, v57, s90
	v_add_u32_e32 v57, 0x3cc00, v60
	global_store_short_d16_hi v57, v56, s[0:1]
	v_mov_b64_e32 v[58:59], v[54:55]
	v_mov_b64_e32 v[56:57], v[52:53]
	s_cbranch_scc1 .LBB0_522
	v_add_u32_e32 v56, 0x30000, v90
	v_add_u32_e32 v93, 0x30800, v87
	v_add_u32_e32 v63, 0x30000, v87
	v_add_u32_e32 v90, 0x30400, v87
	global_load_dwordx4 v[56:59], v56, s[84:85]
	s_nop 0
	global_load_ushort v91, v63, s[4:5]
	global_load_ushort v92, v90, s[4:5]
	s_nop 0
	global_load_ushort v93, v93, s[4:5]
	v_add_u32_e32 v63, 0x30c00, v87
	global_load_ushort v94, v63, s[4:5]
	s_branch .LBB0_522
	s_nop 0
	s_nop 0

.LBB0_594:
	s_or_b64 exec, exec, s[10:11]
	v_readlane_b32 s10, v254, 15
	v_lshlrev_b32_e32 v98, 11, v161
	s_add_u32 s10, s10, s18
	v_readlane_b32 s11, v254, 16
	v_and_b32_e32 v97, 8, v49
	v_lshl_or_b32 v49, s26, 9, v98
	s_addc_u32 s11, s11, s19
	v_lshlrev_b32_e32 v82, 8, v89
	v_mov_b32_e32 v83, v137
	v_lshlrev_b32_e32 v48, 9, v48
	v_or3_b32 v49, v49, s25, v89
	v_lshl_add_u64 v[32:33], s[10:11], 0, v[82:83]
	v_mov_b32_e32 v75, v137
	v_or3_b32 v48, v48, v97, s25
	v_lshlrev_b32_e32 v49, 1, v49
	v_lshl_add_u64 v[44:45], v[32:33], 0, v[74:75]
	v_lshlrev_b32_e32 v48, 1, v48
	v_add_u32_e32 v50, 0x400, v49
	s_or_b32 s10, s26, 16
	global_load_dwordx4 v[32:35], v[44:45], off
	global_load_dwordx4 v[36:39], v[44:45], off offset:64
	global_load_dwordx4 v[40:43], v[44:45], off offset:128
	s_nop 0
	global_load_dwordx4 v[44:47], v[44:45], off offset:192
	v_add_u32_e32 v51, 0x800, v49
	global_load_dwordx4 v[60:63], v48, s[84:85]
	global_load_ushort v109, v49, s[84:85]
	global_load_ushort v110, v50, s[84:85]
	global_load_ushort v111, v51, s[84:85]
	v_add_u32_e32 v48, 0xc00, v49
	v_or_b32_e32 v49, s10, v89
	v_lshl_or_b32 v50, s10, 9, v98
	v_lshlrev_b32_e32 v49, 9, v49
	v_or3_b32 v50, v50, s25, v89
	v_or3_b32 v49, v49, v97, s25
	v_lshlrev_b32_e32 v50, 1, v50
	v_lshlrev_b32_e32 v49, 1, v49
	v_add_u32_e32 v51, 0x400, v50
	global_load_ushort v112, v48, s[84:85]
	global_load_dwordx4 v[52:55], v49, s[84:85]
	global_load_ushort v100, v50, s[84:85]
	global_load_ushort v101, v51, s[84:85]
	v_add_u32_e32 v48, 0x800, v50
	v_add_u32_e32 v49, 0xc00, v50
	global_load_ushort v102, v48, s[84:85]
	global_load_ushort v103, v49, s[84:85]
	v_lshlrev_b32_e32 v48, 10, v161
	v_lshlrev_b32_e32 v49, 2, v89
	v_add3_u32 v86, s23, v48, v49
	v_mov_b32_e32 v48, s23
	s_movk_i32 s10, 0x110
	v_mad_u32_u24 v48, v89, s10, v48
	s_lshl_b32 s10, s14, 21
	s_lshl_b32 s11, s22, 18
	v_add_u32_e32 v87, s23, v56
	s_add_i32 s10, s10, s11
	v_lshlrev_b32_e32 v51, 10, v89
	v_and_b32_e32 v56, 16, v160
	v_lshlrev_b32_e32 v50, 1, v89
	v_or3_b32 v90, s10, v51, v56
	v_lshlrev_b32_e32 v51, 12, v161
	v_and_b32_e32 v49, 48, v88
	v_or3_b32 v91, s10, v51, v50
	v_add_u32_e32 v92, v48, v49
	v_mov_b32_e32 v65, v91
	v_mov_b32_e32 v67, v90
	s_branch .LBB0_596
	s_nop 0
	s_nop 0
	s_nop 0
	s_nop 0
	s_nop 0
	s_nop 0
	s_nop 0
	s_nop 0
	s_nop 0
	s_nop 0
	s_nop 0
	s_nop 0
	s_nop 0
	s_nop 0

.LBB0_600:
	v_cndmask_b32_e64 v59, 0, v63, s[8:9]
	v_cndmask_b32_e64 v58, 0, v62, s[8:9]
	v_cndmask_b32_e64 v57, 0, v61, s[8:9]
	v_cndmask_b32_e64 v56, 0, v60, s[8:9]
	v_lshlrev_b32_e32 v114, 16, v109
	v_lshlrev_b32_e32 v105, 16, v112
	v_mfma_f32_16x16x32_bf16 v[60:63], v[56:59], v[4:7], 0
	v_lshlrev_b32_e32 v112, 16, v111
	v_lshlrev_b32_e32 v113, 16, v110
	s_cmp_gt_u32 s6, 12
	v_mfma_f32_16x16x32_bf16 v[106:109], v[56:59], v[0:3], 0
	s_nop 7
	v_cvt_pkrtz_f16_f32 v93, v60, v106
	v_cvt_pkrtz_f16_f32 v94, v61, v107
	v_cvt_pkrtz_f16_f32 v95, v62, v108
	v_cvt_pkrtz_f16_f32 v96, v63, v109
	v_mfma_f32_16x16x32_bf16 v[60:63], v[56:59], v[12:15], 0
	v_mfma_f32_16x16x32_bf16 v[106:109], v[56:59], v[8:11], 0
	s_nop 7
	v_cvt_pkrtz_f16_f32 v60, v60, v106
	ds_write2_b32 v86, v93, v60 offset1:16
	v_cvt_pkrtz_f16_f32 v60, v61, v107
	ds_write2_b32 v86, v94, v60 offset0:64 offset1:80
	v_cvt_pkrtz_f16_f32 v60, v62, v108
	ds_write2_b32 v86, v95, v60 offset0:128 offset1:144
	v_cvt_pkrtz_f16_f32 v60, v63, v109
	ds_write2_b32 v86, v96, v60 offset0:192 offset1:208
	v_mfma_f32_16x16x32_bf16 v[60:63], v[56:59], v[20:23], 0
	v_mfma_f32_16x16x32_bf16 v[106:109], v[56:59], v[16:19], 0
	s_nop 7
	v_cvt_pkrtz_f16_f32 v93, v60, v106
	v_cvt_pkrtz_f16_f32 v94, v61, v107
	v_cvt_pkrtz_f16_f32 v95, v62, v108
	v_cvt_pkrtz_f16_f32 v96, v63, v109
	v_mfma_f32_16x16x32_bf16 v[60:63], v[56:59], v[28:31], 0
	v_mfma_f32_16x16x32_bf16 v[56:59], v[56:59], v[24:27], 0
	s_nop 7
	v_cvt_pkrtz_f16_f32 v56, v60, v56
	ds_write2_b32 v86, v93, v56 offset0:32 offset1:48
	v_cvt_pkrtz_f16_f32 v56, v61, v57
	ds_write2_b32 v86, v94, v56 offset0:96 offset1:112
	v_cvt_pkrtz_f16_f32 v56, v62, v58
	ds_write2_b32 v86, v95, v56 offset0:160 offset1:176
	v_cvt_pkrtz_f16_f32 v56, v63, v59
	ds_write2_b32 v86, v96, v56 offset0:224 offset1:240
	ds_read2st64_b32 v[56:57], v87 offset1:1
	ds_read2st64_b32 v[58:59], v87 offset0:2 offset1:3
	ds_read2st64_b32 v[60:61], v87 offset0:4 offset1:5
	ds_read2st64_b32 v[62:63], v87 offset0:6 offset1:7
	ds_read2st64_b32 v[94:95], v87 offset0:8 offset1:9
	ds_read2st64_b32 v[106:107], v87 offset0:10 offset1:11
	ds_read2st64_b32 v[108:109], v87 offset0:12 offset1:13
	ds_read2st64_b32 v[110:111], v87 offset0:14 offset1:15
	s_waitcnt lgkmcnt(7)
	v_fma_mix_f32 v93, v84, v80, v56 op_sel_hi:[0,0,1]
	v_fma_mix_f32 v56, v84, v81, v56 op_sel:[0,0,1] op_sel_hi:[0,0,1]
	v_fma_f32 v81, -v85, v81, v93
	v_fmac_f32_e32 v56, v85, v80
	s_nop 0
	v_fma_mix_f32 v93, v84, v81, v57 op_sel_hi:[0,0,1]
	v_fma_mix_f32 v57, v84, v56, v57 op_sel:[0,0,1] op_sel_hi:[0,0,1]
	v_cvt_pk_bf16_f32 v80, v81, v56
	v_fma_f32 v56, -v85, v56, v93
	v_fmac_f32_e32 v57, v85, v81
	s_waitcnt lgkmcnt(6)
	v_fma_mix_f32 v93, v84, v56, v58 op_sel_hi:[0,0,1]
	v_fma_mix_f32 v58, v84, v57, v58 op_sel:[0,0,1] op_sel_hi:[0,0,1]
	v_cvt_pk_bf16_f32 v81, v56, v57
	v_fma_f32 v57, -v85, v57, v93
	v_fmac_f32_e32 v58, v85, v56
	s_nop 0
	v_fma_mix_f32 v93, v84, v57, v59 op_sel_hi:[0,0,1]
	v_fma_mix_f32 v59, v84, v58, v59 op_sel:[0,0,1] op_sel_hi:[0,0,1]
	v_cvt_pk_bf16_f32 v56, v57, v58
	v_fma_f32 v58, -v85, v58, v93
	v_fmac_f32_e32 v59, v85, v57
	s_waitcnt lgkmcnt(5)
	v_fma_mix_f32 v93, v84, v58, v60 op_sel_hi:[0,0,1]
	v_fma_mix_f32 v60, v84, v59, v60 op_sel:[0,0,1] op_sel_hi:[0,0,1]
	v_cvt_pk_bf16_f32 v57, v58, v59
	v_fma_f32 v59, -v85, v59, v93
	v_fmac_f32_e32 v60, v85, v58
	s_nop 0
	v_fma_mix_f32 v93, v84, v59, v61 op_sel_hi:[0,0,1]
	v_fma_mix_f32 v61, v84, v60, v61 op_sel:[0,0,1] op_sel_hi:[0,0,1]
	v_cvt_pk_bf16_f32 v58, v59, v60
	v_fma_f32 v60, -v85, v60, v93
	v_fmac_f32_e32 v61, v85, v59
	s_waitcnt lgkmcnt(4)
	v_fma_mix_f32 v93, v84, v60, v62 op_sel_hi:[0,0,1]
	v_fma_mix_f32 v62, v84, v61, v62 op_sel:[0,0,1] op_sel_hi:[0,0,1]
	v_cvt_pk_bf16_f32 v59, v60, v61
	v_fma_f32 v61, -v85, v61, v93
	v_fmac_f32_e32 v62, v85, v60
	s_nop 0
	v_fma_mix_f32 v60, v84, v61, v63 op_sel_hi:[0,0,1]
	v_fma_mix_f32 v63, v84, v62, v63 op_sel:[0,0,1] op_sel_hi:[0,0,1]
	v_fma_f32 v60, -v85, v62, v60
	v_fmac_f32_e32 v63, v85, v61
	v_cvt_pk_bf16_f32 v96, v61, v62
	s_waitcnt lgkmcnt(3)
	v_fma_mix_f32 v61, v84, v60, v94 op_sel_hi:[0,0,1]
	v_fma_mix_f32 v93, v84, v63, v94 op_sel:[0,0,1] op_sel_hi:[0,0,1]
	v_fma_f32 v61, -v85, v63, v61
	v_fmac_f32_e32 v93, v85, v60
	v_cvt_pk_bf16_f32 v62, v60, v63
	s_nop 0
	v_fma_mix_f32 v60, v84, v61, v95 op_sel_hi:[0,0,1]
	v_fma_mix_f32 v94, v84, v93, v95 op_sel:[0,0,1] op_sel_hi:[0,0,1]
	v_fma_f32 v60, -v85, v93, v60
	v_fmac_f32_e32 v94, v85, v61
	v_cvt_pk_bf16_f32 v63, v61, v93
	v_add_u32_e32 v95, 0x2800, v87
	s_waitcnt lgkmcnt(2)
	v_fma_mix_f32 v61, v84, v60, v106 op_sel_hi:[0,0,1]
	v_fma_mix_f32 v93, v84, v94, v106 op_sel:[0,0,1] op_sel_hi:[0,0,1]
	v_fma_f32 v61, -v85, v94, v61
	v_fmac_f32_e32 v93, v85, v60
	v_cvt_pk_bf16_f32 v115, v60, v94
	s_nop 0
	v_fma_mix_f32 v60, v84, v61, v107 op_sel_hi:[0,0,1]
	v_fma_mix_f32 v94, v84, v93, v107 op_sel:[0,0,1] op_sel_hi:[0,0,1]
	v_fma_f32 v60, -v85, v93, v60
	v_fmac_f32_e32 v94, v85, v61
	v_cvt_pk_bf16_f32 v106, v61, v93
	s_waitcnt lgkmcnt(1)
	v_fma_mix_f32 v61, v84, v60, v108 op_sel_hi:[0,0,1]
	v_fma_mix_f32 v93, v84, v94, v108 op_sel:[0,0,1] op_sel_hi:[0,0,1]
	v_fma_f32 v61, -v85, v94, v61
	v_fmac_f32_e32 v93, v85, v60
	v_cvt_pk_bf16_f32 v107, v60, v94
	s_nop 0
	v_fma_mix_f32 v60, v84, v61, v109 op_sel_hi:[0,0,1]
	v_fma_mix_f32 v94, v84, v93, v109 op_sel:[0,0,1] op_sel_hi:[0,0,1]
	v_fma_f32 v60, -v85, v93, v60
	v_fmac_f32_e32 v94, v85, v61
	v_cvt_pk_bf16_f32 v108, v61, v93
	s_waitcnt lgkmcnt(0)
	v_fma_mix_f32 v61, v84, v60, v110 op_sel_hi:[0,0,1]
	v_fma_mix_f32 v93, v84, v94, v110 op_sel:[0,0,1] op_sel_hi:[0,0,1]
	v_cvt_pk_bf16_f32 v109, v60, v94
	v_fma_f32 v94, -v85, v94, v61
	v_fmac_f32_e32 v93, v85, v60
	s_nop 0
	v_fma_mix_f32 v60, v84, v94, v111 op_sel_hi:[0,0,1]
	v_fma_mix_f32 v61, v84, v93, v111 op_sel:[0,0,1] op_sel_hi:[0,0,1]
	v_cvt_pk_bf16_f32 v110, v94, v93
	v_fma_f32 v60, -v85, v93, v60
	v_fmac_f32_e32 v61, v85, v94
	v_add_u32_e32 v93, 0x2000, v87
	v_add_u32_e32 v94, 0x2400, v87
	s_nop 0
	v_cvt_pk_bf16_f32 v111, v60, v61
	ds_write2_b32 v93, v80, v81 offset1:68
	ds_write2_b32 v93, v56, v57 offset0:136 offset1:204
	ds_write2_b32 v94, v58, v59 offset0:16 offset1:84
	ds_write2_b32 v94, v96, v62 offset0:152 offset1:220
	v_add_u32_e32 v96, 0x2c00, v87
	ds_write2_b32 v95, v63, v115 offset0:32 offset1:100
	ds_write2_b32 v95, v106, v107 offset0:168 offset1:236
	ds_write2_b32 v96, v108, v109 offset0:48 offset1:116
	ds_write2_b32 v96, v110, v111 offset0:184 offset1:252
	ds_read_b128 v[56:59], v92 offset:8192
	ds_read_b128 v[106:109], v92 offset:8256
	s_waitcnt lgkmcnt(1)
	v_mfma_f32_16x16x32_bf16 v[56:59], v[56:59], v[32:35], 0
	s_waitcnt lgkmcnt(0)
	v_mfma_f32_16x16x32_bf16 v[56:59], v[106:109], v[36:39], v[56:59]
	ds_read_b128 v[106:109], v92 offset:8320
	s_waitcnt lgkmcnt(0)
	v_mfma_f32_16x16x32_bf16 v[56:59], v[106:109], v[40:43], v[56:59]
	ds_read_b128 v[106:109], v92 offset:8384
	s_waitcnt lgkmcnt(0)
	v_mfma_f32_16x16x32_bf16 v[56:59], v[106:109], v[44:47], v[56:59]
	s_waitcnt vmcnt(0)
	v_mov_b32_e32 v108, v103
	v_mov_b32_e32 v107, v102
	v_mov_b32_e32 v106, v101
	s_nop 3
	v_fma_f32 v56, v163, v114, v56
	v_bfe_u32 v62, v56, 16, 1
	v_add3_u32 v56, v56, v62, s90
	v_add_u32_e32 v62, 0x400000, v69
	global_store_short_d16_hi v62, v56, s[4:5]
	v_fma_f32 v56, v163, v113, v57
	v_bfe_u32 v57, v56, 16, 1
	v_add3_u32 v56, v56, v57, s90
	v_add_u32_e32 v57, 0x400400, v69
	global_store_short_d16_hi v57, v56, s[4:5]
	v_fma_f32 v56, v163, v112, v58
	v_bfe_u32 v57, v56, 16, 1
	v_add3_u32 v56, v56, v57, s90
	v_add_u32_e32 v57, 0x400800, v69
	v_fmac_f32_e32 v59, v163, v105
	global_store_short_d16_hi v57, v56, s[4:5]
	v_bfe_u32 v56, v59, 16, 1
	v_add3_u32 v56, v59, v56, s90
	v_add_u32_e32 v57, 0x400c00, v69
	global_store_short_d16_hi v57, v56, s[4:5]
	v_mov_b64_e32 v[58:59], v[54:55]
	v_mov_b32_e32 v105, v100
	v_mov_b64_e32 v[56:57], v[52:53]
	s_cbranch_scc1 .LBB0_595
	v_add_u32_e32 v56, 0x40c000, v104
	v_add_u32_e32 v62, 0x40c000, v69
	v_add_u32_e32 v63, 0x40c400, v69
	v_add_u32_e32 v80, 0x40c800, v69
	global_load_dwordx4 v[56:59], v56, s[84:85]
	s_nop 0
	global_load_ushort v105, v62, s[84:85]
	global_load_ushort v106, v63, s[84:85]
	global_load_ushort v107, v80, s[84:85]
	v_add_u32_e32 v62, 0x40cc00, v69
	global_load_ushort v108, v62, s[84:85]
	s_branch .LBB0_595
	s_nop 0
	s_nop 0

.LBB0_618:
	s_or_b64 exec, exec, s[10:11]
	v_readlane_b32 s10, v254, 15
	s_add_u32 s2, s10, s2
	v_readlane_b32 s10, v254, 16
	s_addc_u32 s3, s10, s3
	v_lshl_add_u64 v[32:33], s[2:3], 0, v[82:83]
	s_or_b32 s2, s26, 0xf0
	v_or_b32_e32 v48, s2, v89
	v_lshl_or_b32 v49, s2, 9, v98
	v_lshlrev_b32_e32 v48, 9, v48
	v_or3_b32 v49, v49, s25, v89
	v_mov_b32_e32 v75, v137
	v_or3_b32 v48, v48, v97, s25
	v_lshlrev_b32_e32 v49, 1, v49
	v_lshl_add_u64 v[44:45], v[32:33], 0, v[74:75]
	v_lshlrev_b32_e32 v48, 1, v48
	v_add_u32_e32 v50, 0x400, v49
	s_or_b32 s2, s26, 0xe0
	global_load_dwordx4 v[32:35], v[44:45], off
	global_load_dwordx4 v[36:39], v[44:45], off offset:64
	global_load_dwordx4 v[40:43], v[44:45], off offset:128
	s_nop 0
	global_load_dwordx4 v[44:47], v[44:45], off offset:192
	v_add_u32_e32 v51, 0x800, v49
	global_load_dwordx4 v[60:63], v48, s[84:85]
	global_load_ushort v82, v49, s[4:5]
	global_load_ushort v83, v50, s[4:5]
	global_load_ushort v84, v51, s[4:5]
	v_add_u32_e32 v48, 0xc00, v49
	v_or_b32_e32 v49, s2, v89
	v_lshl_or_b32 v50, s2, 9, v98
	v_lshlrev_b32_e32 v49, 9, v49
	v_or3_b32 v50, v50, s25, v89
	v_or3_b32 v49, v49, v97, s25
	v_lshlrev_b32_e32 v50, 1, v50
	v_lshlrev_b32_e32 v49, 1, v49
	v_add_u32_e32 v51, 0x400, v50
	global_load_ushort v85, v48, s[4:5]
	global_load_dwordx4 v[52:55], v49, s[84:85]
	global_load_ushort v70, v50, s[4:5]
	global_load_ushort v71, v51, s[4:5]
	v_add_u32_e32 v48, 0x800, v50
	v_add_u32_e32 v49, 0xc00, v50
	global_load_ushort v72, v48, s[4:5]
	global_load_ushort v73, v49, s[4:5]
	v_mov_b32_e32 v65, v78
	s_branch .LBB0_620
	s_nop 0
	s_nop 0
	s_nop 0
	s_nop 0
	s_nop 0
	s_nop 0
	s_nop 0
	s_nop 0
	s_nop 0
	s_nop 0
	s_nop 0
	s_nop 0
	s_nop 0
	s_nop 0

.LBB0_624:
	v_cndmask_b32_e64 v63, 0, v63, s[8:9]
	v_cndmask_b32_e64 v62, 0, v62, s[8:9]
	v_cndmask_b32_e64 v61, 0, v61, s[8:9]
	v_cndmask_b32_e64 v60, 0, v60, s[8:9]
	v_lshlrev_b32_e32 v56, 16, v85
	v_lshlrev_b32_e32 v57, 16, v84
	v_lshlrev_b32_e32 v77, 16, v83
	v_lshlrev_b32_e32 v78, 16, v82
	v_mfma_f32_16x16x32_bf16 v[82:85], v[60:63], v[4:7], 0
	s_cmp_gt_u32 s6, 12
	v_mfma_f32_16x16x32_bf16 v[98:101], v[60:63], v[0:3], 0
	s_nop 7
	v_cvt_pkrtz_f16_f32 v58, v82, v98
	v_cvt_pkrtz_f16_f32 v59, v83, v99
	v_cvt_pkrtz_f16_f32 v74, v84, v100
	v_cvt_pkrtz_f16_f32 v75, v85, v101
	v_mfma_f32_16x16x32_bf16 v[82:85], v[60:63], v[12:15], 0
	v_mfma_f32_16x16x32_bf16 v[98:101], v[60:63], v[8:11], 0
	s_nop 7
	v_cvt_pkrtz_f16_f32 v82, v82, v98
	ds_write2_b32 v86, v58, v82 offset1:16
	v_cvt_pkrtz_f16_f32 v58, v83, v99
	ds_write2_b32 v86, v59, v58 offset0:64 offset1:80
	v_cvt_pkrtz_f16_f32 v58, v84, v100
	ds_write2_b32 v86, v74, v58 offset0:128 offset1:144
	v_cvt_pkrtz_f16_f32 v58, v85, v101
	v_mfma_f32_16x16x32_bf16 v[82:85], v[60:63], v[20:23], 0
	ds_write2_b32 v86, v75, v58 offset0:192 offset1:208
	v_mfma_f32_16x16x32_bf16 v[98:101], v[60:63], v[16:19], 0
	s_nop 7
	v_cvt_pkrtz_f16_f32 v74, v82, v98
	v_cvt_pkrtz_f16_f32 v75, v83, v99
	v_cvt_pkrtz_f16_f32 v89, v84, v100
	v_cvt_pkrtz_f16_f32 v97, v85, v101
	v_mfma_f32_16x16x32_bf16 v[82:85], v[60:63], v[28:31], 0
	v_mfma_f32_16x16x32_bf16 v[58:61], v[60:63], v[24:27], 0
	s_nop 7
	v_cvt_pkrtz_f16_f32 v58, v82, v58
	ds_write2_b32 v86, v74, v58 offset0:32 offset1:48
	v_cvt_pkrtz_f16_f32 v58, v83, v59
	ds_write2_b32 v86, v75, v58 offset0:96 offset1:112
	v_cvt_pkrtz_f16_f32 v58, v84, v60
	ds_write2_b32 v86, v89, v58 offset0:160 offset1:176
	v_cvt_pkrtz_f16_f32 v58, v85, v61
	ds_write2_b32 v86, v97, v58 offset0:224 offset1:240
	ds_read2st64_b32 v[58:59], v87 offset0:14 offset1:15
	ds_read2st64_b32 v[60:61], v87 offset0:12 offset1:13
	ds_read2st64_b32 v[62:63], v87 offset0:10 offset1:11
	ds_read2st64_b32 v[74:75], v87 offset0:8 offset1:9
	ds_read2st64_b32 v[82:83], v87 offset0:6 offset1:7
	ds_read2st64_b32 v[84:85], v87 offset0:4 offset1:5
	ds_read2st64_b32 v[98:99], v87 offset0:2 offset1:3
	ds_read2st64_b32 v[100:101], v87 offset1:1
	s_waitcnt lgkmcnt(7)
	v_fma_mix_f32 v89, v80, v65, v59 op_sel_hi:[0,0,1]
	v_fma_mix_f32 v59, v80, v79, v59 op_sel:[0,0,1] op_sel_hi:[0,0,1]
	v_fma_f32 v79, -v81, v79, v89
	v_fmac_f32_e32 v59, v81, v65
	s_nop 0
	v_fma_mix_f32 v89, v80, v79, v58 op_sel_hi:[0,0,1]
	v_fma_mix_f32 v58, v80, v59, v58 op_sel:[0,0,1] op_sel_hi:[0,0,1]
	v_cvt_pk_bf16_f32 v65, v79, v59
	v_fma_f32 v59, -v81, v59, v89
	v_fmac_f32_e32 v58, v81, v79
	s_waitcnt lgkmcnt(6)
	v_fma_mix_f32 v89, v80, v59, v61 op_sel_hi:[0,0,1]
	v_fma_mix_f32 v61, v80, v58, v61 op_sel:[0,0,1] op_sel_hi:[0,0,1]
	v_cvt_pk_bf16_f32 v79, v59, v58
	v_fma_f32 v58, -v81, v58, v89
	v_fmac_f32_e32 v61, v81, v59
	s_nop 0
	v_fma_mix_f32 v89, v80, v58, v60 op_sel_hi:[0,0,1]
	v_fma_mix_f32 v60, v80, v61, v60 op_sel:[0,0,1] op_sel_hi:[0,0,1]
	v_cvt_pk_bf16_f32 v59, v58, v61
	v_fma_f32 v61, -v81, v61, v89
	v_fmac_f32_e32 v60, v81, v58
	s_waitcnt lgkmcnt(5)
	v_fma_mix_f32 v89, v80, v61, v63 op_sel_hi:[0,0,1]
	v_fma_mix_f32 v63, v80, v60, v63 op_sel:[0,0,1] op_sel_hi:[0,0,1]
	v_cvt_pk_bf16_f32 v58, v61, v60
	v_fma_f32 v60, -v81, v60, v89
	v_fmac_f32_e32 v63, v81, v61
	s_nop 0
	v_fma_mix_f32 v61, v80, v60, v62 op_sel_hi:[0,0,1]
	v_fma_mix_f32 v62, v80, v63, v62 op_sel:[0,0,1] op_sel_hi:[0,0,1]
	v_fma_f32 v61, -v81, v63, v61
	v_fmac_f32_e32 v62, v81, v60
	v_cvt_pk_bf16_f32 v89, v60, v63
	s_waitcnt lgkmcnt(4)
	v_fma_mix_f32 v60, v80, v61, v75 op_sel_hi:[0,0,1]
	v_fma_mix_f32 v75, v80, v62, v75 op_sel:[0,0,1] op_sel_hi:[0,0,1]
	v_fma_f32 v60, -v81, v62, v60
	v_fmac_f32_e32 v75, v81, v61
	v_cvt_pk_bf16_f32 v63, v61, v62
	s_nop 0
	v_fma_mix_f32 v61, v80, v60, v74 op_sel_hi:[0,0,1]
	v_fma_mix_f32 v74, v80, v75, v74 op_sel:[0,0,1] op_sel_hi:[0,0,1]
	v_fma_f32 v61, -v81, v75, v61
	v_fmac_f32_e32 v74, v81, v60
	v_cvt_pk_bf16_f32 v62, v60, v75
	s_waitcnt lgkmcnt(3)
	v_fma_mix_f32 v60, v80, v61, v83 op_sel_hi:[0,0,1]
	v_fma_mix_f32 v83, v80, v74, v83 op_sel:[0,0,1] op_sel_hi:[0,0,1]
	v_fma_f32 v60, -v81, v74, v60
	v_fmac_f32_e32 v83, v81, v61
	v_cvt_pk_bf16_f32 v75, v61, v74
	s_nop 0
	v_fma_mix_f32 v61, v80, v60, v82 op_sel_hi:[0,0,1]
	v_fma_mix_f32 v82, v80, v83, v82 op_sel:[0,0,1] op_sel_hi:[0,0,1]
	v_fma_f32 v61, -v81, v83, v61
	v_fmac_f32_e32 v82, v81, v60
	v_cvt_pk_bf16_f32 v74, v60, v83
	s_waitcnt lgkmcnt(2)
	v_fma_mix_f32 v60, v80, v61, v85 op_sel_hi:[0,0,1]
	v_fma_mix_f32 v85, v80, v82, v85 op_sel:[0,0,1] op_sel_hi:[0,0,1]
	v_fma_f32 v60, -v81, v82, v60
	v_fmac_f32_e32 v85, v81, v61
	v_cvt_pk_bf16_f32 v83, v61, v82
	s_nop 0
	v_fma_mix_f32 v61, v80, v60, v84 op_sel_hi:[0,0,1]
	v_fma_mix_f32 v84, v80, v85, v84 op_sel:[0,0,1] op_sel_hi:[0,0,1]
	v_fma_f32 v61, -v81, v85, v61
	v_fmac_f32_e32 v84, v81, v60
	v_cvt_pk_bf16_f32 v82, v60, v85
	s_waitcnt lgkmcnt(1)
	v_fma_mix_f32 v60, v80, v61, v99 op_sel_hi:[0,0,1]
	v_fma_mix_f32 v97, v80, v84, v99 op_sel:[0,0,1] op_sel_hi:[0,0,1]
	v_fma_f32 v60, -v81, v84, v60
	v_fmac_f32_e32 v97, v81, v61
	v_cvt_pk_bf16_f32 v85, v61, v84
	s_nop 0
	v_fma_mix_f32 v61, v80, v60, v98 op_sel_hi:[0,0,1]
	v_fma_mix_f32 v98, v80, v97, v98 op_sel:[0,0,1] op_sel_hi:[0,0,1]
	v_fma_f32 v61, -v81, v97, v61
	v_fmac_f32_e32 v98, v81, v60
	v_cvt_pk_bf16_f32 v84, v60, v97
	s_waitcnt lgkmcnt(0)
	v_fma_mix_f32 v60, v80, v61, v101 op_sel_hi:[0,0,1]
	v_fma_mix_f32 v99, v80, v98, v101 op_sel:[0,0,1] op_sel_hi:[0,0,1]
	v_cvt_pk_bf16_f32 v97, v61, v98
	v_fma_f32 v98, -v81, v98, v60
	v_fmac_f32_e32 v99, v81, v61
	s_nop 0
	v_fma_mix_f32 v60, v80, v98, v100 op_sel_hi:[0,0,1]
	v_fma_mix_f32 v61, v80, v99, v100 op_sel:[0,0,1] op_sel_hi:[0,0,1]
	v_fma_f32 v60, -v81, v99, v60
	v_fmac_f32_e32 v61, v81, v98
	v_cvt_pk_bf16_f32 v101, v98, v99
	s_nop 0
	v_cvt_pk_bf16_f32 v98, v60, v61
	ds_write2_b32 v96, v79, v65 offset0:184 offset1:252
	ds_write2_b32 v96, v58, v59 offset0:48 offset1:116
	ds_write2_b32 v95, v63, v89 offset0:168 offset1:236
	ds_write2_b32 v95, v75, v62 offset0:32 offset1:100
	ds_write2_b32 v94, v83, v74 offset0:152 offset1:220
	ds_write2_b32 v94, v85, v82 offset0:16 offset1:84
	ds_write2_b32 v93, v97, v84 offset0:136 offset1:204
	ds_write2_b32 v93, v98, v101 offset1:68
	ds_read_b128 v[82:85], v92 offset:8192
	ds_read_b128 v[98:101], v92 offset:8256
	s_waitcnt lgkmcnt(1)
	v_mfma_f32_16x16x32_bf16 v[82:85], v[82:85], v[32:35], 0
	s_waitcnt vmcnt(2)
	v_mov_b32_e32 v75, v71
	v_mov_b32_e32 v74, v70
	s_waitcnt lgkmcnt(0)
	v_mfma_f32_16x16x32_bf16 v[82:85], v[98:101], v[36:39], v[82:85]
	ds_read_b128 v[98:101], v92 offset:8320
	s_waitcnt lgkmcnt(0)
	v_mfma_f32_16x16x32_bf16 v[82:85], v[98:101], v[40:43], v[82:85]
	ds_read_b128 v[98:101], v92 offset:8384
	s_waitcnt lgkmcnt(0)
	v_mfma_f32_16x16x32_bf16 v[82:85], v[98:101], v[44:47], v[82:85]
	s_nop 7
	v_add_f32_e32 v58, v82, v78
	v_mul_f32_e32 v59, 0x3d372713, v58
	v_mul_f32_e32 v59, v58, v59
	v_fma_f32 v59, v58, v59, v58
	v_mul_f32_e32 v59, 0x3f4c422a, v59
	v_add_f32_e32 v59, v59, v59
	v_mul_f32_e32 v59, 0xbfb8aa3b, v59
	v_exp_f32_e32 v59, v59
	v_add_f32_e32 v57, v84, v57
	v_add_f32_e32 v56, v85, v56
	s_waitcnt vmcnt(0)
	v_mov_b32_e32 v78, v73
	v_add_f32_e32 v59, 1.0, v59
	v_rcp_f32_e32 v59, v59
	s_nop 0
	v_mul_f32_e32 v58, v58, v59
	v_bfe_u32 v59, v58, 16, 1
	v_add3_u32 v58, v58, v59, s90
	v_add_u32_e32 v59, 0x43c000, v66
	global_store_short_d16_hi v59, v58, s[0:1]
	v_add_f32_e32 v58, v83, v77
	v_mul_f32_e32 v59, 0x3d372713, v58
	v_mul_f32_e32 v59, v58, v59
	v_fma_f32 v59, v58, v59, v58
	v_mul_f32_e32 v59, 0x3f4c422a, v59
	v_add_f32_e32 v59, v59, v59
	v_mul_f32_e32 v59, 0xbfb8aa3b, v59
	v_exp_f32_e32 v59, v59
	v_mov_b32_e32 v77, v72
	v_add_f32_e32 v59, 1.0, v59
	v_rcp_f32_e32 v59, v59
	s_nop 0
	v_mul_f32_e32 v58, v58, v59
	v_bfe_u32 v59, v58, 16, 1
	v_add3_u32 v58, v58, v59, s90
	v_add_u32_e32 v59, 0x43c400, v66
	global_store_short_d16_hi v59, v58, s[0:1]
	v_mul_f32_e32 v58, 0x3d372713, v57
	v_mul_f32_e32 v58, v57, v58
	v_fma_f32 v58, v57, v58, v57
	v_mul_f32_e32 v58, 0x3f4c422a, v58
	v_add_f32_e32 v58, v58, v58
	v_mul_f32_e32 v58, 0xbfb8aa3b, v58
	v_exp_f32_e32 v58, v58
	s_nop 0
	v_add_f32_e32 v58, 1.0, v58
	v_rcp_f32_e32 v58, v58
	s_nop 0
	v_mul_f32_e32 v57, v57, v58
	v_bfe_u32 v58, v57, 16, 1
	v_add3_u32 v57, v57, v58, s90
	v_add_u32_e32 v58, 0x43c800, v66
	global_store_short_d16_hi v58, v57, s[0:1]
	v_mul_f32_e32 v57, 0x3d372713, v56
	v_mul_f32_e32 v57, v56, v57
	v_fma_f32 v57, v56, v57, v56
	v_mul_f32_e32 v57, 0x3f4c422a, v57
	v_add_f32_e32 v57, v57, v57
	v_mul_f32_e32 v57, 0xbfb8aa3b, v57
	v_exp_f32_e32 v57, v57
	s_nop 0
	v_add_f32_e32 v57, 1.0, v57
	v_rcp_f32_e32 v57, v57
	s_nop 0
	v_mul_f32_e32 v56, v56, v57
	v_bfe_u32 v57, v56, 16, 1
	v_add3_u32 v56, v56, v57, s90
	v_add_u32_e32 v57, 0x43cc00, v66
	global_store_short_d16_hi v57, v56, s[0:1]
	v_mov_b64_e32 v[58:59], v[54:55]
	v_mov_b64_e32 v[56:57], v[52:53]
	s_cbranch_scc1 .LBB0_619
	v_add_u32_e32 v56, 0x430000, v76
	v_add_u32_e32 v62, 0x430000, v66
	v_add_u32_e32 v63, 0x430400, v66
	v_add_u32_e32 v65, 0x430800, v66
	global_load_dwordx4 v[56:59], v56, s[84:85]
	s_nop 0
	global_load_ushort v74, v62, s[4:5]
	global_load_ushort v75, v63, s[4:5]
	global_load_ushort v77, v65, s[4:5]
	v_add_u32_e32 v62, 0x430c00, v66
	global_load_ushort v78, v62, s[4:5]
	s_branch .LBB0_619
	s_nop 0
	s_nop 0
